# w_up activation epilogue: remaining 47 dead DPP-destination zero-initialisations turned into s_nop 0 (same wait state, no VALU slot)
# speedup vs baseline: 1.0117x; 1.0007x over previous
.LBB0_378:
	v_mov_b32_e32 v184, v149
	v_mov_b32_e32 v185, v150
	v_mov_b32_e32 v149, v151
	v_pk_add_f32 v[148:149], v[184:185], v[148:149]
	v_cmp_eq_u32_e64 s[8:9], 0, v212
	v_add_f32_e32 v148, v148, v149
	v_fmamk_f32 v148, v148, 0x3a800000, v241
	v_rsq_f32_e32 v226, v148
	v_mov_b32_e32 v148, v145
	v_mov_b32_e32 v149, v146
	v_mov_b32_e32 v145, v147
	v_pk_add_f32 v[144:145], v[148:149], v[144:145]
	s_nop 0
	v_add_f32_e32 v144, v144, v145
	v_fmamk_f32 v144, v144, 0x3a800000, v241
	v_rsq_f32_e32 v224, v144
	v_mov_b32_e32 v144, v153
	v_mov_b32_e32 v145, v154
	v_mov_b32_e32 v153, v155
	v_pk_add_f32 v[144:145], v[144:145], v[152:153]
	s_nop 0
	v_add_f32_e32 v144, v144, v145
	v_fmamk_f32 v144, v144, 0x3a800000, v241
	v_rsq_f32_e32 v222, v144
	v_pk_mul_f32 v[144:145], v[140:141], v[226:227] op_sel_hi:[1,0]
	v_pk_mul_f32 v[140:141], v[128:129], v[226:227] op_sel_hi:[1,0]
	v_pk_mul_f32 v[128:129], v[136:137], v[224:225] op_sel_hi:[1,0]
	v_pk_mul_f32 v[136:137], v[126:127], v[224:225] op_sel_hi:[1,0]
	v_pk_mul_f32 v[126:127], v[134:135], v[222:223] op_sel_hi:[1,0]
	v_pk_mul_f32 v[134:135], v[132:133], v[222:223] op_sel_hi:[1,0]
	v_mov_b32_e32 v132, v218
	v_mov_b32_e32 v133, v218
	v_mov_b32_e32 v219, v218
	v_pk_mul_f32 v[118:119], v[118:119], v[132:133]
	s_waitcnt vmcnt(2)
	v_cndmask_b32_e64 v132, v172, v176, s[8:9]
	v_cndmask_b32_e64 v133, v173, v177, s[8:9]
	v_mov_b32_dpp v148, v144 row_ror:1 row_mask:0xf bank_mask:0xf
	v_mov_b32_dpp v149, v145 row_ror:1 row_mask:0xf bank_mask:0xf
	v_mov_b32_dpp v150, v144 row_ror:2 row_mask:0xf bank_mask:0xf
	v_mov_b32_dpp v151, v145 row_ror:2 row_mask:0xf bank_mask:0xf
	v_cmp_lt_u32_e64 s[10:11], 1, v212
	v_pk_mul_f32 v[146:147], v[142:143], v[226:227] op_sel_hi:[1,0]
	v_pk_mul_f32 v[142:143], v[130:131], v[226:227] op_sel_hi:[1,0]
	v_pk_mul_f32 v[130:131], v[138:139], v[224:225] op_sel_hi:[1,0]
	v_pk_mul_f32 v[138:139], v[116:117], v[218:219]
	v_cndmask_b32_e64 v117, v149, v173, s[8:9]
	v_cndmask_b32_e64 v116, v148, v172, s[8:9]
	v_cndmask_b32_e64 v133, v133, v151, s[10:11]
	v_cndmask_b32_e64 v132, v132, v150, s[10:11]
	v_pk_mul_f32 v[132:133], v[156:157], v[132:133]
	v_mov_b32_dpp v172, v128 row_ror:2 row_mask:0xf bank_mask:0xf
	v_mov_b32_dpp v173, v129 row_ror:2 row_mask:0xf bank_mask:0xf
	s_waitcnt vmcnt(1)
	v_pk_fma_f32 v[116:117], v[160:161], v[116:117], v[132:133]
	v_mov_b32_dpp v154, v128 row_ror:1 row_mask:0xf bank_mask:0xf
	v_mov_b32_dpp v155, v129 row_ror:1 row_mask:0xf bank_mask:0xf
	v_cndmask_b32_e64 v151, v151, v173, s[10:11]
	v_cndmask_b32_e64 v150, v150, v172, s[10:11]
	s_waitcnt vmcnt(0)
	v_pk_fma_f32 v[116:117], v[144:145], v[164:165], v[116:117]
	v_cndmask_b32_e64 v149, v155, v149, s[8:9]
	v_cndmask_b32_e64 v148, v154, v148, s[8:9]
	v_pk_mul_f32 v[150:151], v[156:157], v[150:151]
	v_pk_mul_f32 v[132:133], v[116:117], s[56:57] op_sel_hi:[1,0]
	v_pk_fma_f32 v[148:149], v[160:161], v[148:149], v[150:151]
	v_exp_f32_e32 v132, v132
	v_exp_f32_e32 v133, v133
	v_pk_fma_f32 v[148:149], v[128:129], v[164:165], v[148:149]
	v_pk_mul_f32 v[124:125], v[124:125], v[224:225] op_sel_hi:[1,0]
	v_pk_mul_f32 v[150:151], v[148:149], s[56:57] op_sel_hi:[1,0]
	v_pk_add_f32 v[132:133], v[132:133], 1.0 op_sel_hi:[1,0]
	v_exp_f32_e32 v150, v150
	v_exp_f32_e32 v151, v151
	v_rcp_f32_e32 v132, v132
	v_rcp_f32_e32 v133, v133
	v_cndmask_b32_e64 v152, v169, v181, s[8:9]
	v_pk_add_f32 v[150:151], v[150:151], 1.0 op_sel_hi:[1,0]
	v_cndmask_b32_e64 v153, v168, v180, s[8:9]
	v_rcp_f32_e32 v150, v150
	v_rcp_f32_e32 v151, v151
	v_pk_mul_f32 v[116:117], v[116:117], v[132:133]
	v_cndmask_b32_e64 v133, v153, v172, s[6:7]
	v_pk_mul_f32 v[116:117], v[140:141], v[116:117]
	s_nop 0
	v_cvt_pk_bf16_f32 v132, v116, v117
	v_pk_mul_f32 v[116:117], v[148:149], v[150:151]
	v_cndmask_b32_e64 v148, v152, v173, s[6:7]
	v_pk_mul_f32 v[116:117], v[124:125], v[116:117]
	s_nop 0
	v_cvt_pk_bf16_f32 v116, v116, v117
	v_cndmask_b32_e64 v117, v168, v154, s[6:7]
	v_cndmask_b32_e64 v124, v169, v155, s[6:7]
	v_mov_b32_dpp v150, v134 row_ror:1 row_mask:0xf bank_mask:0xf
	v_mov_b32_dpp v151, v135 row_ror:1 row_mask:0xf bank_mask:0xf
	v_mov_b32_dpp v152, v134 row_ror:2 row_mask:0xf bank_mask:0xf
	v_mov_b32_dpp v153, v135 row_ror:2 row_mask:0xf bank_mask:0xf
	v_cndmask_b32_e64 v125, v151, v124, s[8:9]
	v_cndmask_b32_e64 v124, v150, v117, s[8:9]
	v_cndmask_b32_e64 v149, v148, v153, s[10:11]
	v_cndmask_b32_e64 v148, v133, v152, s[10:11]
	v_pk_mul_f32 v[148:149], v[156:157], v[148:149]
	v_mov_b32_dpp v117, v108 row_ror:1 row_mask:0xf bank_mask:0xf
	v_mov_b32_dpp v133, v109 row_ror:1 row_mask:0xf bank_mask:0xf
	v_mov_b32_dpp v154, v108 row_ror:2 row_mask:0xf bank_mask:0xf
	v_mov_b32_dpp v155, v109 row_ror:2 row_mask:0xf bank_mask:0xf
	v_pk_fma_f32 v[124:125], v[160:161], v[124:125], v[148:149]
	v_cndmask_b32_e64 v149, v133, v151, s[8:9]
	v_cndmask_b32_e64 v148, v117, v150, s[8:9]
	v_cndmask_b32_e64 v151, v153, v155, s[10:11]
	v_cndmask_b32_e64 v150, v152, v154, s[10:11]
	v_pk_fma_f32 v[124:125], v[134:135], v[164:165], v[124:125]
	v_pk_mul_f32 v[150:151], v[156:157], v[150:151]
	v_pk_mul_f32 v[134:135], v[124:125], s[56:57] op_sel_hi:[1,0]
	v_pk_fma_f32 v[148:149], v[160:161], v[148:149], v[150:151]
	v_exp_f32_e32 v134, v134
	v_exp_f32_e32 v135, v135
	v_pk_fma_f32 v[148:149], v[108:109], v[164:165], v[148:149]
	v_pk_mul_f32 v[120:121], v[120:121], v[222:223] op_sel_hi:[1,0]
	v_pk_mul_f32 v[150:151], v[148:149], s[56:57] op_sel_hi:[1,0]
	v_pk_add_f32 v[134:135], v[134:135], 1.0 op_sel_hi:[1,0]
	v_exp_f32_e32 v150, v150
	v_exp_f32_e32 v151, v151
	v_rcp_f32_e32 v134, v134
	v_rcp_f32_e32 v135, v135
	v_cndmask_b32_e64 v117, v174, v178, s[8:9]
	v_pk_add_f32 v[150:151], v[150:151], 1.0 op_sel_hi:[1,0]
	s_nop 0
	v_rcp_f32_e32 v150, v150
	v_rcp_f32_e32 v151, v151
	v_pk_mul_f32 v[124:125], v[124:125], v[134:135]
	v_mov_b32_dpp v133, v146 row_ror:1 row_mask:0xf bank_mask:0xf
	v_pk_mul_f32 v[120:121], v[120:121], v[124:125]
	s_nop 0
	v_cvt_pk_bf16_f32 v124, v120, v121
	v_pk_mul_f32 v[120:121], v[148:149], v[150:151]
	s_nop 0
	v_pk_mul_f32 v[120:121], v[138:139], v[120:121]
	s_nop 0
	v_cvt_pk_bf16_f32 v120, v120, v121
	v_cndmask_b32_e64 v121, v175, v179, s[8:9]
	v_mov_b32_dpp v150, v146 row_ror:2 row_mask:0xf bank_mask:0xf
	v_mov_b32_dpp v151, v147 row_ror:2 row_mask:0xf bank_mask:0xf
	v_mov_b32_dpp v148, v147 row_ror:1 row_mask:0xf bank_mask:0xf
	v_cndmask_b32_e64 v139, v121, v151, s[10:11]
	v_cndmask_b32_e64 v138, v117, v150, s[10:11]
	v_cndmask_b32_e64 v135, v148, v175, s[8:9]
	v_cndmask_b32_e64 v134, v133, v174, s[8:9]
	v_pk_mul_f32 v[138:139], v[158:159], v[138:139]
	v_mov_b32_dpp v154, v130 row_ror:2 row_mask:0xf bank_mask:0xf
	v_mov_b32_dpp v155, v131 row_ror:2 row_mask:0xf bank_mask:0xf
	v_pk_fma_f32 v[134:135], v[162:163], v[134:135], v[138:139]
	v_mov_b32_dpp v121, v130 row_ror:1 row_mask:0xf bank_mask:0xf
	v_mov_b32_dpp v153, v131 row_ror:1 row_mask:0xf bank_mask:0xf
	v_cndmask_b32_e64 v151, v151, v155, s[10:11]
	v_cndmask_b32_e64 v150, v150, v154, s[10:11]
	v_pk_fma_f32 v[134:135], v[146:147], v[166:167], v[134:135]
	v_cndmask_b32_e64 v149, v153, v148, s[8:9]
	v_cndmask_b32_e64 v148, v121, v133, s[8:9]
	v_pk_mul_f32 v[150:151], v[158:159], v[150:151]
	v_pk_mul_f32 v[138:139], v[134:135], s[56:57] op_sel_hi:[1,0]
	v_pk_fma_f32 v[148:149], v[162:163], v[148:149], v[150:151]
	v_exp_f32_e32 v138, v138
	v_exp_f32_e32 v139, v139
	v_pk_fma_f32 v[148:149], v[130:131], v[166:167], v[148:149]
	v_cndmask_b32_e64 v125, v171, v183, s[8:9]
	v_pk_mul_f32 v[150:151], v[148:149], s[56:57] op_sel_hi:[1,0]
	v_pk_add_f32 v[138:139], v[138:139], 1.0 op_sel_hi:[1,0]
	v_exp_f32_e32 v150, v150
	v_exp_f32_e32 v151, v151
	v_rcp_f32_e32 v138, v138
	v_rcp_f32_e32 v139, v139
	v_cndmask_b32_e64 v152, v170, v182, s[8:9]
	v_pk_add_f32 v[150:151], v[150:151], 1.0 op_sel_hi:[1,0]
	v_cndmask_b32_e64 v121, v170, v121, s[6:7]
	v_rcp_f32_e32 v150, v150
	v_rcp_f32_e32 v151, v151
	v_pk_mul_f32 v[134:135], v[134:135], v[138:139]
	s_nop 0
	v_pk_mul_f32 v[134:135], v[142:143], v[134:135]
	s_nop 0
	v_cvt_pk_bf16_f32 v133, v134, v135
	v_pk_mul_f32 v[134:135], v[148:149], v[150:151]
	s_nop 0
	v_pk_mul_f32 v[134:135], v[136:137], v[134:135]
	s_nop 0
	v_cvt_pk_bf16_f32 v117, v134, v135
	v_cndmask_b32_e64 v134, v171, v153, s[6:7]
	v_cndmask_b32_e64 v136, v152, v154, s[6:7]
	v_cndmask_b32_e64 v125, v125, v155, s[6:7]
	v_mov_b32_dpp v138, v126 row_ror:1 row_mask:0xf bank_mask:0xf
	v_mov_b32_dpp v139, v127 row_ror:1 row_mask:0xf bank_mask:0xf
	v_mov_b32_dpp v148, v126 row_ror:2 row_mask:0xf bank_mask:0xf
	v_mov_b32_dpp v149, v127 row_ror:2 row_mask:0xf bank_mask:0xf
	v_cndmask_b32_e64 v135, v139, v134, s[8:9]
	v_cndmask_b32_e64 v134, v138, v121, s[8:9]
	v_cndmask_b32_e64 v137, v125, v149, s[10:11]
	v_cndmask_b32_e64 v136, v136, v148, s[10:11]
	v_pk_mul_f32 v[136:137], v[158:159], v[136:137]
	v_mov_b32_dpp v121, v110 row_ror:1 row_mask:0xf bank_mask:0xf
	v_mov_b32_dpp v125, v111 row_ror:1 row_mask:0xf bank_mask:0xf
	v_mov_b32_dpp v150, v110 row_ror:2 row_mask:0xf bank_mask:0xf
	v_mov_b32_dpp v151, v111 row_ror:2 row_mask:0xf bank_mask:0xf
	v_pk_fma_f32 v[134:135], v[162:163], v[134:135], v[136:137]
	v_cndmask_b32_e64 v137, v125, v139, s[8:9]
	v_cndmask_b32_e64 v136, v121, v138, s[8:9]
	v_cndmask_b32_e64 v139, v149, v151, s[10:11]
	v_cndmask_b32_e64 v138, v148, v150, s[10:11]
	v_pk_fma_f32 v[126:127], v[126:127], v[166:167], v[134:135]
	v_pk_mul_f32 v[138:139], v[158:159], v[138:139]
	v_pk_mul_f32 v[134:135], v[126:127], s[56:57] op_sel_hi:[1,0]
	v_pk_fma_f32 v[136:137], v[162:163], v[136:137], v[138:139]
	v_exp_f32_e32 v134, v134
	v_exp_f32_e32 v135, v135
	v_pk_fma_f32 v[136:137], v[110:111], v[166:167], v[136:137]
	v_pk_mul_f32 v[122:123], v[122:123], v[222:223] op_sel_hi:[1,0]
	v_pk_mul_f32 v[138:139], v[136:137], s[56:57] op_sel_hi:[1,0]
	v_pk_add_f32 v[134:135], v[134:135], 1.0 op_sel_hi:[1,0]
	v_exp_f32_e32 v138, v138
	v_exp_f32_e32 v139, v139
	v_rcp_f32_e32 v134, v134
	v_rcp_f32_e32 v135, v135
	s_cmp_eq_u32 s21, 0
	v_pk_add_f32 v[138:139], v[138:139], 1.0 op_sel_hi:[1,0]
	s_cselect_b64 s[28:29], -1, 0
	v_rcp_f32_e32 v138, v138
	v_rcp_f32_e32 v139, v139
	v_pk_mul_f32 v[126:127], v[126:127], v[134:135]
	s_nop 0
	v_pk_mul_f32 v[122:123], v[122:123], v[126:127]
	s_nop 0
	v_cvt_pk_bf16_f32 v125, v122, v123
	v_pk_mul_f32 v[122:123], v[136:137], v[138:139]
	s_nop 0
	v_pk_mul_f32 v[118:119], v[118:119], v[122:123]
	s_nop 0
	v_cvt_pk_bf16_f32 v121, v118, v119
	v_add_co_u32_e32 v118, vcc, 0x2000, v210
	s_nop 1
	v_addc_co_u32_e32 v119, vcc, 0, v211, vcc
	global_load_dwordx4 v[148:151], v[210:211], off offset:16
	global_load_dwordx4 v[152:155], v[118:119], off offset:3088
	v_add_co_u32_e32 v118, vcc, 0x5000, v210
	s_nop 1
	v_addc_co_u32_e32 v119, vcc, 0, v211, vcc
	global_load_dwordx4 v[156:159], v[118:119], off offset:2064
	ds_read_b128 v[172:175], v2 offset:16
	ds_read_b128 v[160:163], v2 offset:528
	v_cndmask_b32_e64 v2, 0, 1, s[2:3]
	v_cmp_ne_u32_e64 s[12:13], 1, v2
	s_andn2_b64 vcc, exec, s[2:3]
	s_cbranch_vccnz .LBB0_380
	s_add_u32 s2, s59, s1
	s_addc_u32 s3, s52, s50
	v_lshl_add_u64 v[118:119], v[206:207], 2, s[2:3]
	v_add_co_u32_e32 v122, vcc, 0x2000, v118
	s_mov_b64 s[28:29], 0
	s_nop 0
	v_addc_co_u32_e32 v123, vcc, 0, v119, vcc
	global_load_dwordx4 v[168:171], v[118:119], off offset:16
	global_load_dwordx4 v[164:167], v[122:123], off offset:3088
	v_add_co_u32_e32 v122, vcc, 0x5000, v118
	s_nop 1
	v_addc_co_u32_e32 v123, vcc, 0, v119, vcc
	v_add_co_u32_e32 v118, vcc, 0x8000, v118
	s_nop 1
	v_addc_co_u32_e32 v119, vcc, 0, v119, vcc
	s_waitcnt lgkmcnt(1)
	global_load_dwordx4 v[172:175], v[122:123], off offset:2064
	s_waitcnt lgkmcnt(0)
	global_load_dwordx4 v[160:163], v[118:119], off offset:1040
	s_branch .LBB0_381

.LBB0_381:
	v_mov_b32_e32 v118, v226
	v_mov_b32_e32 v119, v226
	v_mov_b32_e32 v227, v226
	v_pk_mul_f32 v[94:95], v[94:95], v[118:119]
	v_pk_mul_f32 v[138:139], v[82:83], v[118:119]
	v_mov_b32_e32 v118, v224
	v_mov_b32_e32 v119, v224
	v_mov_b32_e32 v225, v224
	v_pk_mul_f32 v[92:93], v[92:93], v[226:227]
	v_pk_mul_f32 v[82:83], v[90:91], v[118:119]
	v_pk_mul_f32 v[78:79], v[78:79], v[118:119]
	v_mov_b32_e32 v90, v222
	v_mov_b32_e32 v91, v222
	v_pk_mul_f32 v[136:137], v[80:81], v[226:227]
	v_pk_mul_f32 v[80:81], v[88:89], v[224:225]
	v_pk_mul_f32 v[88:89], v[76:77], v[224:225]
	v_pk_mul_f32 v[76:77], v[86:87], v[90:91]
	v_pk_mul_f32 v[74:75], v[74:75], v[90:91]
	v_mov_b32_e32 v86, v218
	v_mov_b32_e32 v87, v218
	s_waitcnt vmcnt(2)
	v_cndmask_b32_e64 v2, v164, v168, s[8:9]
	v_cndmask_b32_e64 v90, v165, v169, s[8:9]
	v_mov_b32_dpp v118, v92 row_ror:1 row_mask:0xf bank_mask:0xf
	v_mov_b32_dpp v119, v93 row_ror:1 row_mask:0xf bank_mask:0xf
	v_mov_b32_dpp v122, v92 row_ror:2 row_mask:0xf bank_mask:0xf
	v_mov_b32_dpp v123, v93 row_ror:2 row_mask:0xf bank_mask:0xf
	v_pk_mul_f32 v[70:71], v[70:71], v[86:87]
	v_cndmask_b32_e64 v87, v119, v165, s[8:9]
	v_cndmask_b32_e64 v86, v118, v164, s[8:9]
	v_cndmask_b32_e64 v91, v90, v123, s[10:11]
	v_cndmask_b32_e64 v90, v2, v122, s[10:11]
	v_pk_mul_f32 v[90:91], v[148:149], v[90:91]
	v_mov_b32_dpp v164, v80 row_ror:2 row_mask:0xf bank_mask:0xf
	v_mov_b32_dpp v165, v81 row_ror:2 row_mask:0xf bank_mask:0xf
	s_waitcnt vmcnt(1)
	v_pk_fma_f32 v[86:87], v[152:153], v[86:87], v[90:91]
	v_mov_b32_dpp v2, v80 row_ror:1 row_mask:0xf bank_mask:0xf
	v_mov_b32_dpp v135, v81 row_ror:1 row_mask:0xf bank_mask:0xf
	v_cndmask_b32_e64 v123, v123, v165, s[10:11]
	v_cndmask_b32_e64 v122, v122, v164, s[10:11]
	s_waitcnt vmcnt(0)
	v_pk_fma_f32 v[86:87], v[92:93], v[156:157], v[86:87]
	v_cndmask_b32_e64 v119, v135, v119, s[8:9]
	v_cndmask_b32_e64 v118, v2, v118, s[8:9]
	v_pk_mul_f32 v[122:123], v[148:149], v[122:123]
	v_pk_mul_f32 v[90:91], v[86:87], s[56:57] op_sel_hi:[1,0]
	v_pk_fma_f32 v[118:119], v[152:153], v[118:119], v[122:123]
	v_exp_f32_e32 v90, v90
	v_exp_f32_e32 v91, v91
	v_pk_fma_f32 v[118:119], v[80:81], v[156:157], v[118:119]
	v_mov_b32_e32 v223, v222
	v_pk_mul_f32 v[122:123], v[118:119], s[56:57] op_sel_hi:[1,0]
	v_pk_add_f32 v[90:91], v[90:91], 1.0 op_sel_hi:[1,0]
	v_exp_f32_e32 v122, v122
	v_exp_f32_e32 v123, v123
	v_rcp_f32_e32 v90, v90
	v_rcp_f32_e32 v91, v91
	v_pk_mul_f32 v[84:85], v[84:85], v[222:223]
	v_pk_add_f32 v[122:123], v[122:123], 1.0 op_sel_hi:[1,0]
	v_cndmask_b32_e64 v126, v161, v173, s[8:9]
	v_rcp_f32_e32 v122, v122
	v_rcp_f32_e32 v123, v123
	v_pk_mul_f32 v[86:87], v[86:87], v[90:91]
	v_cndmask_b32_e64 v127, v160, v172, s[8:9]
	v_pk_mul_f32 v[86:87], v[136:137], v[86:87]
	s_nop 0
	v_cvt_pk_bf16_f32 v134, v86, v87
	v_pk_mul_f32 v[86:87], v[118:119], v[122:123]
	s_nop 0
	v_pk_mul_f32 v[86:87], v[88:89], v[86:87]
	v_cndmask_b32_e64 v88, v127, v164, s[6:7]
	v_cndmask_b32_e64 v89, v126, v165, s[6:7]
	v_mov_b32_dpp v119, v84 row_ror:2 row_mask:0xf bank_mask:0xf
	v_mov_b32_dpp v122, v85 row_ror:2 row_mask:0xf bank_mask:0xf
	v_cvt_pk_bf16_f32 v118, v86, v87
	v_cndmask_b32_e64 v2, v160, v2, s[6:7]
	v_cndmask_b32_e64 v86, v161, v135, s[6:7]
	v_mov_b32_dpp v90, v84 row_ror:1 row_mask:0xf bank_mask:0xf
	v_mov_b32_dpp v91, v85 row_ror:1 row_mask:0xf bank_mask:0xf
	v_cndmask_b32_e64 v89, v89, v122, s[10:11]
	v_cndmask_b32_e64 v88, v88, v119, s[10:11]
	v_cndmask_b32_e64 v87, v91, v86, s[8:9]
	v_cndmask_b32_e64 v86, v90, v2, s[8:9]
	v_pk_mul_f32 v[88:89], v[148:149], v[88:89]
	s_nop 0
	v_pk_fma_f32 v[86:87], v[152:153], v[86:87], v[88:89]
	v_mov_b32_dpp v2, v112 row_ror:1 row_mask:0xf bank_mask:0xf
	v_mov_b32_dpp v88, v113 row_ror:1 row_mask:0xf bank_mask:0xf
	v_mov_b32_dpp v123, v112 row_ror:2 row_mask:0xf bank_mask:0xf
	v_mov_b32_dpp v126, v113 row_ror:2 row_mask:0xf bank_mask:0xf
	v_cndmask_b32_e64 v89, v88, v91, s[8:9]
	v_cndmask_b32_e64 v88, v2, v90, s[8:9]
	v_cndmask_b32_e64 v91, v122, v126, s[10:11]
	v_cndmask_b32_e64 v90, v119, v123, s[10:11]
	v_pk_fma_f32 v[84:85], v[84:85], v[156:157], v[86:87]
	v_pk_mul_f32 v[90:91], v[148:149], v[90:91]
	v_pk_mul_f32 v[86:87], v[84:85], s[56:57] op_sel_hi:[1,0]
	v_pk_fma_f32 v[88:89], v[152:153], v[88:89], v[90:91]
	v_exp_f32_e32 v86, v86
	v_exp_f32_e32 v87, v87
	v_pk_fma_f32 v[88:89], v[112:113], v[156:157], v[88:89]
	v_pk_mul_f32 v[72:73], v[72:73], v[222:223]
	v_pk_mul_f32 v[90:91], v[88:89], s[56:57] op_sel_hi:[1,0]
	v_pk_add_f32 v[86:87], v[86:87], 1.0 op_sel_hi:[1,0]
	v_exp_f32_e32 v90, v90
	v_exp_f32_e32 v91, v91
	v_rcp_f32_e32 v86, v86
	v_rcp_f32_e32 v87, v87
	v_pk_mul_f32 v[68:69], v[68:69], v[218:219]
	v_pk_add_f32 v[90:91], v[90:91], 1.0 op_sel_hi:[1,0]
	v_cndmask_b32_e64 v2, v166, v170, s[8:9]
	v_rcp_f32_e32 v90, v90
	v_rcp_f32_e32 v91, v91
	v_pk_mul_f32 v[84:85], v[84:85], v[86:87]
	s_nop 0
	v_pk_mul_f32 v[72:73], v[72:73], v[84:85]
	s_nop 0
	v_cvt_pk_bf16_f32 v126, v72, v73
	v_pk_mul_f32 v[72:73], v[88:89], v[90:91]
	s_nop 0
	v_pk_mul_f32 v[68:69], v[68:69], v[72:73]
	v_cndmask_b32_e64 v72, v167, v171, s[8:9]
	v_mov_b32_dpp v86, v94 row_ror:2 row_mask:0xf bank_mask:0xf
	v_mov_b32_dpp v87, v95 row_ror:2 row_mask:0xf bank_mask:0xf
	v_mov_b32_dpp v84, v94 row_ror:1 row_mask:0xf bank_mask:0xf
	v_mov_b32_dpp v85, v95 row_ror:1 row_mask:0xf bank_mask:0xf
	v_cndmask_b32_e64 v73, v72, v87, s[10:11]
	v_cndmask_b32_e64 v72, v2, v86, s[10:11]
	v_cvt_pk_bf16_f32 v122, v68, v69
	v_cndmask_b32_e64 v69, v85, v167, s[8:9]
	v_cndmask_b32_e64 v68, v84, v166, s[8:9]
	v_pk_mul_f32 v[72:73], v[150:151], v[72:73]
	v_mov_b32_dpp v91, v82 row_ror:2 row_mask:0xf bank_mask:0xf
	v_mov_b32_dpp v123, v83 row_ror:2 row_mask:0xf bank_mask:0xf
	v_pk_fma_f32 v[68:69], v[154:155], v[68:69], v[72:73]
	v_mov_b32_dpp v2, v82 row_ror:1 row_mask:0xf bank_mask:0xf
	v_mov_b32_dpp v90, v83 row_ror:1 row_mask:0xf bank_mask:0xf
	v_cndmask_b32_e64 v87, v87, v123, s[10:11]
	v_cndmask_b32_e64 v86, v86, v91, s[10:11]
	v_pk_fma_f32 v[68:69], v[94:95], v[158:159], v[68:69]
	v_cndmask_b32_e64 v85, v90, v85, s[8:9]
	v_cndmask_b32_e64 v84, v2, v84, s[8:9]
	v_pk_mul_f32 v[86:87], v[150:151], v[86:87]
	v_pk_mul_f32 v[72:73], v[68:69], s[56:57] op_sel_hi:[1,0]
	v_pk_fma_f32 v[84:85], v[154:155], v[84:85], v[86:87]
	v_exp_f32_e32 v72, v72
	v_exp_f32_e32 v73, v73
	v_pk_fma_f32 v[84:85], v[82:83], v[158:159], v[84:85]
	v_cndmask_b32_e64 v88, v163, v175, s[8:9]
	v_pk_mul_f32 v[86:87], v[84:85], s[56:57] op_sel_hi:[1,0]
	v_pk_add_f32 v[72:73], v[72:73], 1.0 op_sel_hi:[1,0]
	v_exp_f32_e32 v86, v86
	v_exp_f32_e32 v87, v87
	v_rcp_f32_e32 v72, v72
	v_rcp_f32_e32 v73, v73
	v_cndmask_b32_e64 v89, v162, v174, s[8:9]
	v_pk_add_f32 v[86:87], v[86:87], 1.0 op_sel_hi:[1,0]
	v_cndmask_b32_e64 v2, v162, v2, s[6:7]
	v_rcp_f32_e32 v86, v86
	v_rcp_f32_e32 v87, v87
	v_pk_mul_f32 v[68:69], v[68:69], v[72:73]
	v_cndmask_b32_e64 v72, v89, v91, s[6:7]
	v_pk_mul_f32 v[68:69], v[138:139], v[68:69]
	v_cndmask_b32_e64 v73, v88, v123, s[6:7]
	v_cvt_pk_bf16_f32 v135, v68, v69
	v_pk_mul_f32 v[68:69], v[84:85], v[86:87]
	s_nop 0
	v_pk_mul_f32 v[68:69], v[78:79], v[68:69]
	v_mov_b32_dpp v84, v76 row_ror:2 row_mask:0xf bank_mask:0xf
	v_mov_b32_dpp v85, v77 row_ror:2 row_mask:0xf bank_mask:0xf
	v_cvt_pk_bf16_f32 v119, v68, v69
	v_cndmask_b32_e64 v68, v163, v90, s[6:7]
	v_mov_b32_dpp v78, v76 row_ror:1 row_mask:0xf bank_mask:0xf
	v_mov_b32_dpp v79, v77 row_ror:1 row_mask:0xf bank_mask:0xf
	v_cndmask_b32_e64 v73, v73, v85, s[10:11]
	v_cndmask_b32_e64 v72, v72, v84, s[10:11]
	v_cndmask_b32_e64 v69, v79, v68, s[8:9]
	v_cndmask_b32_e64 v68, v78, v2, s[8:9]
	v_pk_mul_f32 v[72:73], v[150:151], v[72:73]
	s_nop 0
	v_pk_fma_f32 v[68:69], v[154:155], v[68:69], v[72:73]
	s_nop 0
	v_pk_fma_f32 v[68:69], v[76:77], v[158:159], v[68:69]
	v_mov_b32_dpp v2, v114 row_ror:1 row_mask:0xf bank_mask:0xf
	v_mov_b32_dpp v76, v115 row_ror:1 row_mask:0xf bank_mask:0xf
	v_mov_b32_dpp v86, v114 row_ror:2 row_mask:0xf bank_mask:0xf
	v_mov_b32_dpp v87, v115 row_ror:2 row_mask:0xf bank_mask:0xf
	v_cndmask_b32_e64 v77, v76, v79, s[8:9]
	v_cndmask_b32_e64 v76, v2, v78, s[8:9]
	v_cndmask_b32_e64 v79, v85, v87, s[10:11]
	v_cndmask_b32_e64 v78, v84, v86, s[10:11]
	v_pk_mul_f32 v[78:79], v[150:151], v[78:79]
	v_pk_mul_f32 v[72:73], v[68:69], s[56:57] op_sel_hi:[1,0]
	v_pk_fma_f32 v[76:77], v[154:155], v[76:77], v[78:79]
	v_exp_f32_e32 v72, v72
	v_exp_f32_e32 v73, v73
	v_pk_fma_f32 v[76:77], v[114:115], v[158:159], v[76:77]
	v_cmp_lt_u32_e32 vcc, 1, v212
	v_pk_mul_f32 v[78:79], v[76:77], s[56:57] op_sel_hi:[1,0]
	v_pk_add_f32 v[72:73], v[72:73], 1.0 op_sel_hi:[1,0]
	v_exp_f32_e32 v78, v78
	v_exp_f32_e32 v79, v79
	v_rcp_f32_e32 v72, v72
	v_rcp_f32_e32 v73, v73
	s_xor_b64 s[2:3], s[28:29], -1
	v_pk_add_f32 v[78:79], v[78:79], 1.0 op_sel_hi:[1,0]
	v_add_u32_e32 v176, s35, v213
	v_mbcnt_lo_u32_b32 v252, -1, 0
	v_mbcnt_hi_u32_b32 v252, -1, v252
	v_and_b32_e32 v253, 3, v252
	v_lshrrev_b32_e32 v248, 2, v252
	v_lshlrev_b32_e32 v249, 6, v253
	v_lshl_or_b32 v249, v248, 2, v249
	v_sub_u32_e32 v248, v248, v212
	v_add_u32_e32 v248, v176, v248
	v_lshrrev_b32_e32 v252, 4, v252
	v_sub_u32_e32 v253, v253, v252
	v_lshl_add_u32 v246, v253, 3, v206
	v_ashrrev_i32_e32 v247, 31, v246
	v_lshlrev_b64 v[250:251], 1, v[246:247]
	v_rcp_f32_e32 v78, v78
	v_rcp_f32_e32 v79, v79
	v_pk_mul_f32 v[68:69], v[68:69], v[72:73]
	s_or_b64 s[2:3], s[2:3], vcc
	v_pk_mul_f32 v[68:69], v[74:75], v[68:69]
	s_nop 0
	v_cvt_pk_bf16_f32 v127, v68, v69
	v_pk_mul_f32 v[68:69], v[76:77], v[78:79]
	s_nop 0
	v_pk_mul_f32 v[68:69], v[70:71], v[68:69]
	s_nop 0
	v_cvt_pk_bf16_f32 v123, v68, v69
	s_and_saveexec_b64 s[28:29], s[2:3]
	s_xor_b64 s[2:3], exec, s[28:29]
	s_cbranch_execz .LBB0_383
	v_mov_b64_e32 v[68:69], s[84:85]
	v_mad_i64_i32 v[68:69], s[28:29], v176, s62, v[68:69]
	v_lshl_add_u64 v[68:69], v[206:207], 1, v[68:69]
	global_store_dwordx4 v[68:69], v[132:135], off nt

.LBB0_391:
	v_mov_b32_e32 v114, v105
	v_mov_b32_e32 v115, v106
	v_mov_b32_e32 v105, v107
	v_mov_b32_e32 v106, v101
	v_mov_b32_e32 v107, v102
	v_mov_b32_e32 v101, v103
	v_mov_b32_e32 v102, v97
	v_mov_b32_e32 v103, v98
	v_mov_b32_e32 v97, v99
	v_pk_add_f32 v[104:105], v[114:115], v[104:105]
	v_pk_add_f32 v[100:101], v[106:107], v[100:101]
	v_pk_add_f32 v[96:97], v[102:103], v[96:97]
	v_add_f32_e32 v104, v104, v105
	v_add_f32_e32 v100, v100, v101
	v_add_f32_e32 v96, v96, v97
	v_fmamk_f32 v104, v104, 0x3a800000, v241
	v_fmamk_f32 v100, v100, 0x3a800000, v241
	v_fmamk_f32 v96, v96, 0x3a800000, v241
	v_rsq_f32_e32 v104, v104
	v_rsq_f32_e32 v100, v100
	v_rsq_f32_e32 v96, v96
	v_mov_b32_e32 v209, v208
	v_pk_mul_f32 v[98:99], v[64:65], v[104:105] op_sel_hi:[1,0]
	v_pk_mul_f32 v[64:65], v[54:55], v[104:105] op_sel_hi:[1,0]
	v_pk_mul_f32 v[102:103], v[52:53], v[104:105] op_sel_hi:[1,0]
	v_pk_mul_f32 v[54:55], v[62:63], v[100:101] op_sel_hi:[1,0]
	v_pk_mul_f32 v[52:53], v[60:61], v[100:101] op_sel_hi:[1,0]
	v_pk_mul_f32 v[60:61], v[50:51], v[100:101] op_sel_hi:[1,0]
	v_pk_mul_f32 v[48:49], v[48:49], v[100:101] op_sel_hi:[1,0]
	v_pk_mul_f32 v[58:59], v[58:59], v[96:97] op_sel_hi:[1,0]
	v_pk_mul_f32 v[56:57], v[56:57], v[96:97] op_sel_hi:[1,0]
	v_pk_mul_f32 v[50:51], v[46:47], v[96:97] op_sel_hi:[1,0]
	v_pk_mul_f32 v[62:63], v[44:45], v[96:97] op_sel_hi:[1,0]
	s_waitcnt vmcnt(2)
	v_cndmask_b32_e64 v44, v84, v88, s[8:9]
	v_cndmask_b32_e64 v45, v85, v89, s[8:9]
	s_waitcnt vmcnt(0)
	v_cndmask_b32_e64 v88, v81, v93, s[8:9]
	v_cndmask_b32_e64 v89, v80, v92, s[8:9]
	v_mov_b32_dpp v97, v98 row_ror:2 row_mask:0xf bank_mask:0xf
	v_mov_b32_dpp v101, v99 row_ror:2 row_mask:0xf bank_mask:0xf
	v_mov_b32_dpp v92, v98 row_ror:1 row_mask:0xf bank_mask:0xf
	v_mov_b32_dpp v93, v99 row_ror:1 row_mask:0xf bank_mask:0xf
	v_cndmask_b32_e64 v45, v45, v101, s[10:11]
	v_cndmask_b32_e64 v44, v44, v97, s[10:11]
	v_pk_mul_f32 v[106:107], v[40:41], v[208:209]
	v_cndmask_b32_e64 v41, v93, v85, s[8:9]
	v_cndmask_b32_e64 v40, v92, v84, s[8:9]
	v_pk_mul_f32 v[44:45], v[68:69], v[44:45]
	v_pk_mul_f32 v[66:67], v[66:67], v[104:105] op_sel_hi:[1,0]
	v_pk_fma_f32 v[40:41], v[72:73], v[40:41], v[44:45]
	s_mov_b64 s[26:27], 0x2c10
	v_pk_fma_f32 v[40:41], v[98:99], v[76:77], v[40:41]
	s_nop 0
	v_pk_mul_f32 v[44:45], v[40:41], s[56:57] op_sel_hi:[1,0]
	s_nop 0
	v_exp_f32_e32 v44, v44
	v_exp_f32_e32 v45, v45
	v_mov_b32_dpp v99, v52 row_ror:2 row_mask:0xf bank_mask:0xf
	v_mov_b32_dpp v98, v53 row_ror:1 row_mask:0xf bank_mask:0xf
	v_cndmask_b32_e64 v84, v97, v99, s[10:11]
	v_pk_add_f32 v[44:45], v[44:45], 1.0 op_sel_hi:[1,0]
	v_mov_b32_e32 v46, v208
	v_rcp_f32_e32 v44, v44
	v_rcp_f32_e32 v45, v45
	v_mov_b32_e32 v47, v208
	v_lshl_add_u64 v[108:109], v[210:211], 0, s[26:27]
	s_mov_b64 s[26:27], 0x5810
	v_pk_mul_f32 v[40:41], v[40:41], v[44:45]
	v_cndmask_b32_e64 v45, v98, v93, s[8:9]
	v_pk_mul_f32 v[40:41], v[102:103], v[40:41]
	s_nop 0
	v_cvt_pk_bf16_f32 v40, v40, v41
	v_pk_mul_f32 v[42:43], v[42:43], v[46:47]
	v_mov_b32_dpp v102, v53 row_ror:2 row_mask:0xf bank_mask:0xf
	v_mov_b32_dpp v41, v52 row_ror:1 row_mask:0xf bank_mask:0xf
	v_cndmask_b32_e64 v85, v101, v102, s[10:11]
	v_cndmask_b32_e64 v44, v41, v92, s[8:9]
	v_pk_mul_f32 v[84:85], v[68:69], v[84:85]
	v_cndmask_b32_e64 v41, v80, v41, s[6:7]
	v_pk_fma_f32 v[44:45], v[72:73], v[44:45], v[84:85]
	v_cndmask_b32_e64 v80, v89, v99, s[6:7]
	v_pk_fma_f32 v[44:45], v[52:53], v[76:77], v[44:45]
	s_nop 0
	v_pk_mul_f32 v[84:85], v[44:45], s[56:57] op_sel_hi:[1,0]
	v_lshl_add_u64 v[110:111], v[210:211], 0, s[26:27]
	v_exp_f32_e32 v84, v84
	v_exp_f32_e32 v85, v85
	v_mov_b32_dpp v89, v57 row_ror:2 row_mask:0xf bank_mask:0xf
	s_and_b64 vcc, exec, s[12:13]
	v_pk_add_f32 v[84:85], v[84:85], 1.0 op_sel_hi:[1,0]
	s_nop 0
	v_rcp_f32_e32 v84, v84
	v_rcp_f32_e32 v85, v85
	s_nop 0
	v_pk_mul_f32 v[44:45], v[44:45], v[84:85]
	s_nop 0
	v_pk_mul_f32 v[44:45], v[48:49], v[44:45]
	s_nop 0
	v_cvt_pk_bf16_f32 v44, v44, v45
	v_cndmask_b32_e64 v45, v81, v98, s[6:7]
	v_cndmask_b32_e64 v81, v88, v102, s[6:7]
	v_mov_b32_dpp v84, v56 row_ror:1 row_mask:0xf bank_mask:0xf
	v_mov_b32_dpp v88, v56 row_ror:2 row_mask:0xf bank_mask:0xf
	v_mov_b32_dpp v85, v57 row_ror:1 row_mask:0xf bank_mask:0xf
	v_cndmask_b32_e64 v81, v81, v89, s[10:11]
	v_cndmask_b32_e64 v80, v80, v88, s[10:11]
	v_cndmask_b32_e64 v49, v85, v45, s[8:9]
	v_cndmask_b32_e64 v48, v84, v41, s[8:9]
	v_pk_mul_f32 v[80:81], v[68:69], v[80:81]
	s_nop 0
	v_pk_fma_f32 v[48:49], v[72:73], v[48:49], v[80:81]
	s_nop 0
	v_pk_fma_f32 v[48:49], v[56:57], v[76:77], v[48:49]
	v_mov_b32_dpp v41, v32 row_ror:1 row_mask:0xf bank_mask:0xf
	v_pk_mul_f32 v[56:57], v[48:49], s[56:57] op_sel_hi:[1,0]
	v_mov_b32_dpp v45, v33 row_ror:1 row_mask:0xf bank_mask:0xf
	v_exp_f32_e32 v56, v56
	v_exp_f32_e32 v57, v57
	s_nop 0
	v_pk_add_f32 v[56:57], v[56:57], 1.0 op_sel_hi:[1,0]
	s_nop 0
	v_rcp_f32_e32 v56, v56
	v_rcp_f32_e32 v57, v57
	s_nop 0
	v_pk_mul_f32 v[48:49], v[48:49], v[56:57]
	s_nop 0
	v_pk_mul_f32 v[48:49], v[62:63], v[48:49]
	s_nop 0
	v_cvt_pk_bf16_f32 v48, v48, v49
	v_cndmask_b32_e64 v57, v45, v85, s[8:9]
	v_mov_b32_dpp v62, v33 row_ror:2 row_mask:0xf bank_mask:0xf
	v_mov_b32_dpp v49, v32 row_ror:2 row_mask:0xf bank_mask:0xf
	v_cndmask_b32_e64 v63, v89, v62, s[10:11]
	v_cndmask_b32_e64 v62, v88, v49, s[10:11]
	v_cndmask_b32_e64 v56, v41, v84, s[8:9]
	v_pk_mul_f32 v[62:63], v[68:69], v[62:63]
	v_cndmask_b32_e64 v41, v86, v90, s[8:9]
	v_pk_fma_f32 v[56:57], v[72:73], v[56:57], v[62:63]
	v_cndmask_b32_e64 v45, v87, v91, s[8:9]
	v_pk_fma_f32 v[56:57], v[32:33], v[76:77], v[56:57]
	s_nop 0
	v_pk_mul_f32 v[62:63], v[56:57], s[56:57] op_sel_hi:[1,0]
	s_nop 0
	v_exp_f32_e32 v62, v62
	v_exp_f32_e32 v63, v63
	v_mov_b32_dpp v76, v66 row_ror:2 row_mask:0xf bank_mask:0xf
	v_pk_add_f32 v[62:63], v[62:63], 1.0 op_sel_hi:[1,0]
	v_mov_b32_dpp v77, v67 row_ror:2 row_mask:0xf bank_mask:0xf
	v_rcp_f32_e32 v62, v62
	v_rcp_f32_e32 v63, v63
	v_mov_b32_dpp v72, v66 row_ror:1 row_mask:0xf bank_mask:0xf
	v_mov_b32_dpp v73, v67 row_ror:1 row_mask:0xf bank_mask:0xf
	v_cndmask_b32_e64 v69, v45, v77, s[10:11]
	v_cndmask_b32_e64 v68, v41, v76, s[10:11]
	v_pk_mul_f32 v[56:57], v[56:57], v[62:63]
	v_cndmask_b32_e64 v63, v73, v87, s[8:9]
	v_cndmask_b32_e64 v62, v72, v86, s[8:9]
	v_pk_mul_f32 v[68:69], v[70:71], v[68:69]
	v_pk_mul_f32 v[56:57], v[106:107], v[56:57]
	v_pk_fma_f32 v[62:63], v[74:75], v[62:63], v[68:69]
	s_nop 0
	v_pk_fma_f32 v[62:63], v[66:67], v[78:79], v[62:63]
	s_nop 0
	v_pk_mul_f32 v[66:67], v[62:63], s[56:57] op_sel_hi:[1,0]
	v_mov_b32_dpp v68, v54 row_ror:2 row_mask:0xf bank_mask:0xf
	v_exp_f32_e32 v66, v66
	v_exp_f32_e32 v67, v67
	v_mov_b32_dpp v69, v55 row_ror:2 row_mask:0xf bank_mask:0xf
	v_cvt_pk_bf16_f32 v56, v56, v57
	v_cndmask_b32_e64 v49, v83, v95, s[8:9]
	v_pk_add_f32 v[66:67], v[66:67], 1.0 op_sel_hi:[1,0]
	v_cndmask_b32_e64 v57, v82, v94, s[8:9]
	v_rcp_f32_e32 v66, v66
	v_rcp_f32_e32 v67, v67
	v_cndmask_b32_e64 v57, v57, v68, s[6:7]
	v_cndmask_b32_e64 v49, v49, v69, s[6:7]
	v_pk_mul_f32 v[62:63], v[62:63], v[66:67]
	s_nop 0
	v_pk_mul_f32 v[62:63], v[64:65], v[62:63]
	v_mov_b32_dpp v66, v54 row_ror:1 row_mask:0xf bank_mask:0xf
	v_mov_b32_dpp v67, v55 row_ror:1 row_mask:0xf bank_mask:0xf
	v_cndmask_b32_e64 v65, v77, v69, s[10:11]
	v_cndmask_b32_e64 v64, v76, v68, s[10:11]
	v_cvt_pk_bf16_f32 v41, v62, v63
	v_cndmask_b32_e64 v63, v67, v73, s[8:9]
	v_cndmask_b32_e64 v62, v66, v72, s[8:9]
	v_pk_mul_f32 v[64:65], v[70:71], v[64:65]
	s_nop 0
	v_pk_fma_f32 v[62:63], v[74:75], v[62:63], v[64:65]
	s_nop 0
	v_pk_fma_f32 v[62:63], v[54:55], v[78:79], v[62:63]
	s_nop 0
	v_pk_mul_f32 v[64:65], v[62:63], s[56:57] op_sel_hi:[1,0]
	s_nop 0
	v_exp_f32_e32 v64, v64
	v_exp_f32_e32 v65, v65
	s_nop 0
	v_pk_add_f32 v[64:65], v[64:65], 1.0 op_sel_hi:[1,0]
	s_nop 0
	v_rcp_f32_e32 v64, v64
	v_rcp_f32_e32 v65, v65
	s_nop 0
	v_pk_mul_f32 v[62:63], v[62:63], v[64:65]
	s_nop 0
	v_pk_mul_f32 v[60:61], v[60:61], v[62:63]
	s_nop 0
	v_cvt_pk_bf16_f32 v45, v60, v61
	v_cndmask_b32_e64 v60, v82, v66, s[6:7]
	v_cndmask_b32_e64 v61, v83, v67, s[6:7]
	v_mov_b32_dpp v66, v58 row_ror:2 row_mask:0xf bank_mask:0xf
	v_mov_b32_dpp v67, v59 row_ror:2 row_mask:0xf bank_mask:0xf
	v_mov_b32_dpp v64, v58 row_ror:1 row_mask:0xf bank_mask:0xf
	v_mov_b32_dpp v65, v59 row_ror:1 row_mask:0xf bank_mask:0xf
	v_cndmask_b32_e64 v63, v49, v67, s[10:11]
	v_cndmask_b32_e64 v62, v57, v66, s[10:11]
	v_cndmask_b32_e64 v61, v65, v61, s[8:9]
	v_cndmask_b32_e64 v60, v64, v60, s[8:9]
	v_pk_mul_f32 v[62:63], v[70:71], v[62:63]
	s_nop 0
	v_pk_fma_f32 v[60:61], v[74:75], v[60:61], v[62:63]
	s_nop 0
	v_pk_fma_f32 v[58:59], v[58:59], v[78:79], v[60:61]
	v_mov_b32_dpp v57, v34 row_ror:2 row_mask:0xf bank_mask:0xf
	v_pk_mul_f32 v[60:61], v[58:59], s[56:57] op_sel_hi:[1,0]
	s_nop 0
	v_exp_f32_e32 v60, v60
	v_exp_f32_e32 v61, v61
	s_nop 0
	v_pk_add_f32 v[60:61], v[60:61], 1.0 op_sel_hi:[1,0]
	s_nop 0
	v_rcp_f32_e32 v60, v60
	v_rcp_f32_e32 v61, v61
	s_nop 0
	v_pk_mul_f32 v[58:59], v[58:59], v[60:61]
	s_nop 0
	v_pk_mul_f32 v[50:51], v[50:51], v[58:59]
	s_nop 0
	v_cvt_pk_bf16_f32 v49, v50, v51
	v_mov_b32_dpp v58, v35 row_ror:2 row_mask:0xf bank_mask:0xf
	v_mov_b32_dpp v50, v34 row_ror:1 row_mask:0xf bank_mask:0xf
	v_mov_b32_dpp v51, v35 row_ror:1 row_mask:0xf bank_mask:0xf
	v_cndmask_b32_e64 v59, v67, v58, s[10:11]
	v_cndmask_b32_e64 v58, v66, v57, s[10:11]
	v_cndmask_b32_e64 v51, v51, v65, s[8:9]
	v_cndmask_b32_e64 v50, v50, v64, s[8:9]
	v_pk_mul_f32 v[58:59], v[70:71], v[58:59]
	s_nop 0
	v_pk_fma_f32 v[50:51], v[74:75], v[50:51], v[58:59]
	s_nop 0
	v_pk_fma_f32 v[50:51], v[34:35], v[78:79], v[50:51]
	s_nop 0
	v_pk_mul_f32 v[58:59], v[50:51], s[56:57] op_sel_hi:[1,0]
	s_nop 0
	v_exp_f32_e32 v58, v58
	v_exp_f32_e32 v59, v59
	s_nop 0
	v_pk_add_f32 v[58:59], v[58:59], 1.0 op_sel_hi:[1,0]
	s_nop 0
	v_rcp_f32_e32 v58, v58
	v_rcp_f32_e32 v59, v59
	s_nop 0
	v_pk_mul_f32 v[50:51], v[50:51], v[58:59]
	s_nop 0
	v_pk_mul_f32 v[42:43], v[42:43], v[50:51]
	s_nop 0
	v_cvt_pk_bf16_f32 v57, v42, v43
	global_load_dwordx4 v[58:61], v[210:211], off offset:16
	global_load_dwordx4 v[62:65], v[108:109], off
	global_load_dwordx4 v[66:69], v[110:111], off
	ds_read_b128 v[78:81], v112 offset:16
	ds_read_b128 v[70:73], v112 offset:528
	s_waitcnt lgkmcnt(1)
	v_mov_b64_e32 v[84:85], v[80:81]
	s_waitcnt lgkmcnt(0)
	v_mov_b64_e32 v[76:77], v[72:73]
	v_mov_b64_e32 v[74:75], v[70:71]
	v_mov_b64_e32 v[82:83], v[78:79]
	s_cbranch_vccnz .LBB0_393
	s_add_u32 s12, s59, s14
	s_addc_u32 s13, s52, s1
	v_lshl_add_u64 v[42:43], v[206:207], 2, s[12:13]
	v_add_co_u32_e32 v50, vcc, 0x2000, v42
	s_nop 1
	v_addc_co_u32_e32 v51, vcc, 0, v43, vcc
	global_load_dwordx4 v[82:85], v[42:43], off offset:16
	global_load_dwordx4 v[74:77], v[50:51], off offset:3088
	v_add_co_u32_e32 v50, vcc, 0x5000, v42
	s_nop 1
	v_addc_co_u32_e32 v51, vcc, 0, v43, vcc
	v_add_co_u32_e32 v42, vcc, 0x8000, v42
	s_nop 1
	v_addc_co_u32_e32 v43, vcc, 0, v43, vcc
	global_load_dwordx4 v[78:81], v[50:51], off offset:2064
	global_load_dwordx4 v[70:73], v[42:43], off offset:1040
.LBB0_393:
	v_mov_b32_e32 v105, v104
	v_mov_b32_e32 v42, v104
	v_mov_b32_e32 v43, v104
	v_mov_b32_e32 v86, v100
	v_mov_b32_e32 v87, v100
	v_mov_b32_e32 v101, v100
	v_pk_mul_f32 v[50:51], v[28:29], v[104:105]
	v_pk_mul_f32 v[28:29], v[18:19], v[42:43]
	v_pk_mul_f32 v[18:19], v[26:27], v[86:87]
	v_mov_b32_e32 v26, v96
	v_mov_b32_e32 v27, v96
	v_pk_mul_f32 v[30:31], v[30:31], v[42:43]
	v_pk_mul_f32 v[42:43], v[16:17], v[104:105]
	v_pk_mul_f32 v[16:17], v[24:25], v[100:101]
	v_pk_mul_f32 v[24:25], v[12:13], v[100:101]
	v_pk_mul_f32 v[12:13], v[22:23], v[26:27]
	v_pk_mul_f32 v[10:11], v[10:11], v[26:27]
	s_waitcnt vmcnt(2)
	v_cndmask_b32_e64 v26, v74, v82, s[8:9]
	v_cndmask_b32_e64 v27, v75, v83, s[8:9]
	v_pk_mul_f32 v[6:7], v[6:7], v[46:47]
	v_mov_b32_dpp v82, v50 row_ror:2 row_mask:0xf bank_mask:0xf
	v_mov_b32_dpp v83, v51 row_ror:2 row_mask:0xf bank_mask:0xf
	v_mov_b32_dpp v46, v50 row_ror:1 row_mask:0xf bank_mask:0xf
	v_mov_b32_dpp v47, v51 row_ror:1 row_mask:0xf bank_mask:0xf
	v_cndmask_b32_e64 v27, v27, v83, s[10:11]
	v_cndmask_b32_e64 v26, v26, v82, s[10:11]
	v_pk_mul_f32 v[14:15], v[14:15], v[86:87]
	v_cndmask_b32_e64 v23, v47, v75, s[8:9]
	v_cndmask_b32_e64 v22, v46, v74, s[8:9]
	v_pk_mul_f32 v[26:27], v[58:59], v[26:27]
	s_waitcnt vmcnt(1)
	v_pk_fma_f32 v[22:23], v[62:63], v[22:23], v[26:27]
	v_mov_b32_dpp v86, v16 row_ror:2 row_mask:0xf bank_mask:0xf
	v_mov_b32_dpp v87, v17 row_ror:2 row_mask:0xf bank_mask:0xf
	s_waitcnt vmcnt(0)
	v_pk_fma_f32 v[22:23], v[50:51], v[66:67], v[22:23]
	v_mov_b32_dpp v74, v16 row_ror:1 row_mask:0xf bank_mask:0xf
	v_mov_b32_dpp v75, v17 row_ror:1 row_mask:0xf bank_mask:0xf
	v_cndmask_b32_e64 v51, v83, v87, s[10:11]
	v_cndmask_b32_e64 v50, v82, v86, s[10:11]
	v_cndmask_b32_e64 v47, v75, v47, s[8:9]
	v_cndmask_b32_e64 v46, v74, v46, s[8:9]
	v_pk_mul_f32 v[50:51], v[58:59], v[50:51]
	v_pk_mul_f32 v[26:27], v[22:23], s[56:57] op_sel_hi:[1,0]
	v_pk_fma_f32 v[46:47], v[62:63], v[46:47], v[50:51]
	v_exp_f32_e32 v26, v26
	v_exp_f32_e32 v27, v27
	v_pk_fma_f32 v[46:47], v[16:17], v[66:67], v[46:47]
	v_mov_b32_e32 v97, v96
	v_pk_mul_f32 v[50:51], v[46:47], s[56:57] op_sel_hi:[1,0]
	v_pk_add_f32 v[26:27], v[26:27], 1.0 op_sel_hi:[1,0]
	v_exp_f32_e32 v50, v50
	v_exp_f32_e32 v51, v51
	v_rcp_f32_e32 v26, v26
	v_rcp_f32_e32 v27, v27
	v_pk_mul_f32 v[20:21], v[20:21], v[96:97]
	v_pk_add_f32 v[50:51], v[50:51], 1.0 op_sel_hi:[1,0]
	v_cndmask_b32_e64 v79, v71, v79, s[8:9]
	v_rcp_f32_e32 v50, v50
	v_rcp_f32_e32 v51, v51
	v_pk_mul_f32 v[22:23], v[22:23], v[26:27]
	v_cndmask_b32_e64 v78, v70, v78, s[8:9]
	v_pk_mul_f32 v[22:23], v[42:43], v[22:23]
	s_nop 0
	v_cvt_pk_bf16_f32 v42, v22, v23
	v_pk_mul_f32 v[22:23], v[46:47], v[50:51]
	s_nop 0
	v_pk_mul_f32 v[22:23], v[24:25], v[22:23]
	v_cndmask_b32_e64 v24, v78, v86, s[6:7]
	v_cndmask_b32_e64 v25, v79, v87, s[6:7]
	v_mov_b32_dpp v43, v20 row_ror:2 row_mask:0xf bank_mask:0xf
	v_mov_b32_dpp v47, v21 row_ror:2 row_mask:0xf bank_mask:0xf
	v_cvt_pk_bf16_f32 v46, v22, v23
	v_cndmask_b32_e64 v22, v70, v74, s[6:7]
	v_cndmask_b32_e64 v23, v71, v75, s[6:7]
	v_mov_b32_dpp v26, v20 row_ror:1 row_mask:0xf bank_mask:0xf
	v_mov_b32_dpp v27, v21 row_ror:1 row_mask:0xf bank_mask:0xf
	v_cndmask_b32_e64 v25, v25, v47, s[10:11]
	v_cndmask_b32_e64 v24, v24, v43, s[10:11]
	v_cndmask_b32_e64 v23, v27, v23, s[8:9]
	v_cndmask_b32_e64 v22, v26, v22, s[8:9]
	v_pk_mul_f32 v[24:25], v[58:59], v[24:25]
	s_nop 0
	v_pk_fma_f32 v[22:23], v[62:63], v[22:23], v[24:25]
	v_mov_b32_dpp v24, v36 row_ror:1 row_mask:0xf bank_mask:0xf
	v_mov_b32_dpp v25, v37 row_ror:1 row_mask:0xf bank_mask:0xf
	v_mov_b32_dpp v50, v36 row_ror:2 row_mask:0xf bank_mask:0xf
	v_mov_b32_dpp v51, v37 row_ror:2 row_mask:0xf bank_mask:0xf
	v_cndmask_b32_e64 v25, v25, v27, s[8:9]
	v_cndmask_b32_e64 v24, v24, v26, s[8:9]
	v_cndmask_b32_e64 v27, v47, v51, s[10:11]
	v_cndmask_b32_e64 v26, v43, v50, s[10:11]
	v_pk_fma_f32 v[20:21], v[20:21], v[66:67], v[22:23]
	v_pk_mul_f32 v[26:27], v[58:59], v[26:27]
	v_pk_mul_f32 v[22:23], v[20:21], s[56:57] op_sel_hi:[1,0]
	v_pk_fma_f32 v[24:25], v[62:63], v[24:25], v[26:27]
	v_exp_f32_e32 v22, v22
	v_exp_f32_e32 v23, v23
	v_pk_fma_f32 v[24:25], v[36:37], v[66:67], v[24:25]
	v_pk_mul_f32 v[8:9], v[8:9], v[96:97]
	v_pk_mul_f32 v[26:27], v[24:25], s[56:57] op_sel_hi:[1,0]
	v_pk_add_f32 v[22:23], v[22:23], 1.0 op_sel_hi:[1,0]
	v_exp_f32_e32 v26, v26
	v_exp_f32_e32 v27, v27
	v_rcp_f32_e32 v22, v22
	v_rcp_f32_e32 v23, v23
	v_pk_mul_f32 v[4:5], v[4:5], v[208:209]
	v_pk_add_f32 v[26:27], v[26:27], 1.0 op_sel_hi:[1,0]
	v_pk_mul_f32 v[20:21], v[20:21], v[22:23]
	v_rcp_f32_e32 v26, v26
	v_rcp_f32_e32 v27, v27
	v_pk_mul_f32 v[8:9], v[8:9], v[20:21]
	s_nop 0
	v_cvt_pk_bf16_f32 v50, v8, v9
	v_pk_mul_f32 v[8:9], v[24:25], v[26:27]
	s_nop 0
	v_pk_mul_f32 v[4:5], v[4:5], v[8:9]
	v_cndmask_b32_e64 v8, v76, v84, s[8:9]
	v_cndmask_b32_e64 v9, v77, v85, s[8:9]
	v_mov_b32_dpp v22, v30 row_ror:2 row_mask:0xf bank_mask:0xf
	v_mov_b32_dpp v23, v31 row_ror:2 row_mask:0xf bank_mask:0xf
	v_mov_b32_dpp v20, v30 row_ror:1 row_mask:0xf bank_mask:0xf
	v_mov_b32_dpp v21, v31 row_ror:1 row_mask:0xf bank_mask:0xf
	v_cndmask_b32_e64 v9, v9, v23, s[10:11]
	v_cndmask_b32_e64 v8, v8, v22, s[10:11]
	v_cvt_pk_bf16_f32 v58, v4, v5
	v_cndmask_b32_e64 v5, v21, v77, s[8:9]
	v_cndmask_b32_e64 v4, v20, v76, s[8:9]
	v_pk_mul_f32 v[8:9], v[60:61], v[8:9]
	s_nop 0
	v_pk_fma_f32 v[4:5], v[64:65], v[4:5], v[8:9]
	s_nop 0
	v_pk_fma_f32 v[4:5], v[30:31], v[68:69], v[4:5]
	v_mov_b32_dpp v26, v18 row_ror:1 row_mask:0xf bank_mask:0xf
	v_mov_b32_dpp v30, v18 row_ror:2 row_mask:0xf bank_mask:0xf
	v_mov_b32_dpp v31, v19 row_ror:2 row_mask:0xf bank_mask:0xf
	v_mov_b32_dpp v27, v19 row_ror:1 row_mask:0xf bank_mask:0xf
	v_cndmask_b32_e64 v23, v23, v31, s[10:11]
	v_cndmask_b32_e64 v22, v22, v30, s[10:11]
	v_cndmask_b32_e64 v21, v27, v21, s[8:9]
	v_cndmask_b32_e64 v20, v26, v20, s[8:9]
	v_pk_mul_f32 v[22:23], v[60:61], v[22:23]
	v_pk_mul_f32 v[8:9], v[4:5], s[56:57] op_sel_hi:[1,0]
	v_pk_fma_f32 v[20:21], v[64:65], v[20:21], v[22:23]
	v_exp_f32_e32 v8, v8
	v_exp_f32_e32 v9, v9
	v_pk_fma_f32 v[20:21], v[18:19], v[68:69], v[20:21]
	v_cndmask_b32_e64 v24, v73, v81, s[8:9]
	v_pk_mul_f32 v[22:23], v[20:21], s[56:57] op_sel_hi:[1,0]
	v_pk_add_f32 v[8:9], v[8:9], 1.0 op_sel_hi:[1,0]
	v_exp_f32_e32 v22, v22
	v_exp_f32_e32 v23, v23
	v_rcp_f32_e32 v8, v8
	v_rcp_f32_e32 v9, v9
	v_cndmask_b32_e64 v25, v72, v80, s[8:9]
	v_pk_add_f32 v[22:23], v[22:23], 1.0 op_sel_hi:[1,0]
	v_pk_mul_f32 v[4:5], v[4:5], v[8:9]
	v_rcp_f32_e32 v22, v22
	v_rcp_f32_e32 v23, v23
	v_pk_mul_f32 v[4:5], v[28:29], v[4:5]
	v_cndmask_b32_e64 v8, v25, v30, s[6:7]
	v_cvt_pk_bf16_f32 v43, v4, v5
	v_pk_mul_f32 v[4:5], v[20:21], v[22:23]
	s_nop 0
	v_pk_mul_f32 v[4:5], v[14:15], v[4:5]
	v_cndmask_b32_e64 v9, v24, v31, s[6:7]
	v_mov_b32_dpp v20, v12 row_ror:2 row_mask:0xf bank_mask:0xf
	v_mov_b32_dpp v21, v13 row_ror:2 row_mask:0xf bank_mask:0xf
	v_cvt_pk_bf16_f32 v47, v4, v5
	v_cndmask_b32_e64 v4, v72, v26, s[6:7]
	v_cndmask_b32_e64 v5, v73, v27, s[6:7]
	v_mov_b32_dpp v14, v12 row_ror:1 row_mask:0xf bank_mask:0xf
	v_mov_b32_dpp v15, v13 row_ror:1 row_mask:0xf bank_mask:0xf
	v_cndmask_b32_e64 v9, v9, v21, s[10:11]
	v_cndmask_b32_e64 v8, v8, v20, s[10:11]
	v_cndmask_b32_e64 v5, v15, v5, s[8:9]
	v_cndmask_b32_e64 v4, v14, v4, s[8:9]
	v_pk_mul_f32 v[8:9], v[60:61], v[8:9]
	s_nop 0
	v_pk_fma_f32 v[4:5], v[64:65], v[4:5], v[8:9]
	s_nop 0
	v_pk_fma_f32 v[4:5], v[12:13], v[68:69], v[4:5]
	v_mov_b32_dpp v22, v38 row_ror:2 row_mask:0xf bank_mask:0xf
	v_mov_b32_dpp v12, v38 row_ror:1 row_mask:0xf bank_mask:0xf
	v_mov_b32_dpp v13, v39 row_ror:1 row_mask:0xf bank_mask:0xf
	v_mov_b32_dpp v23, v39 row_ror:2 row_mask:0xf bank_mask:0xf
	v_cndmask_b32_e64 v13, v13, v15, s[8:9]
	v_cndmask_b32_e64 v12, v12, v14, s[8:9]
	v_cndmask_b32_e64 v15, v21, v23, s[10:11]
	v_cndmask_b32_e64 v14, v20, v22, s[10:11]
	v_pk_mul_f32 v[14:15], v[60:61], v[14:15]
	v_pk_mul_f32 v[8:9], v[4:5], s[56:57] op_sel_hi:[1,0]
	v_pk_fma_f32 v[12:13], v[64:65], v[12:13], v[14:15]
	v_exp_f32_e32 v8, v8
	v_exp_f32_e32 v9, v9
	v_pk_fma_f32 v[12:13], v[38:39], v[68:69], v[12:13]
	v_pk_add_f32 v[8:9], v[8:9], 1.0 op_sel_hi:[1,0]
	v_pk_mul_f32 v[14:15], v[12:13], s[56:57] op_sel_hi:[1,0]
	v_rcp_f32_e32 v8, v8
	v_exp_f32_e32 v14, v14
	v_exp_f32_e32 v15, v15
	v_rcp_f32_e32 v9, v9
	v_pk_add_f32 v[14:15], v[14:15], 1.0 op_sel_hi:[1,0]
	s_nop 0
	v_rcp_f32_e32 v14, v14
	v_rcp_f32_e32 v15, v15
	v_pk_mul_f32 v[4:5], v[4:5], v[8:9]
	s_nop 0
	v_pk_mul_f32 v[4:5], v[10:11], v[4:5]
	s_nop 0
	v_cvt_pk_bf16_f32 v51, v4, v5
	v_pk_mul_f32 v[4:5], v[12:13], v[14:15]
	s_nop 0
	v_pk_mul_f32 v[4:5], v[6:7], v[4:5]
	v_add_u32_e32 v6, 0x80, v248
	v_cvt_pk_bf16_f32 v59, v4, v5
	v_mov_b64_e32 v[4:5], s[84:85]
	v_mad_i64_i32 v[4:5], s[6:7], v6, s62, v[4:5]
	v_lshl_add_u64 v[4:5], v[246:247], 1, v[4:5]
	v_mov_b32_e32 v236, v4
	v_mov_b32_e32 v237, v5
	ds_bpermute_b32 v228, v249, v40
	ds_bpermute_b32 v229, v249, v41
	ds_bpermute_b32 v230, v249, v42
	ds_bpermute_b32 v231, v249, v43
	s_waitcnt lgkmcnt(4)
	global_store_dwordx4 v[242:243], v[232:235], off nt
	s_and_saveexec_b64 s[6:7], s[2:3]
	s_cbranch_execz .LBB0_395
	s_ashr_i32 s1, s0, 31
	s_lshl_b64 s[8:9], s[0:1], 1
	s_add_u32 s8, s8, 8
	s_addc_u32 s9, s9, 0
	v_lshl_add_u64 v[4:5], s[8:9], 0, v[2:3]
	v_mov_b64_e32 v[6:7], s[70:71]
	v_mad_u64_u32 v[6:7], s[8:9], v4, s67, v[6:7]
	v_mad_i32_i24 v7, v5, s67, v7
	v_lshl_add_u64 v[4:5], v[206:207], 2, v[6:7]
	global_store_dwordx4 v[4:5], v[52:55], off
	global_store_dwordx4 v[4:5], v[16:19], off offset:16
